# build_rtab: all four row batches loaded up front (one L2 round trip instead of four) before reducing
# speedup vs baseline: 1.0040x; 1.0040x over previous
.LBB0_159:
	v_lshl_add_u64 v[34:35], s[26:27], 0, v[0:1]
	global_load_dwordx4 v[6:9], v[34:35], off offset:48
	global_load_dwordx4 v[10:13], v[34:35], off offset:32
	global_load_dwordx4 v[14:17], v[34:35], off
	global_load_dwordx4 v[18:21], v[34:35], off offset:16
	global_load_dwordx4 v[22:25], v[34:35], off offset:112
	global_load_dwordx4 v[26:29], v[34:35], off offset:96
	global_load_dwordx4 v[30:33], v[34:35], off offset:80
	s_nop 0
	global_load_dwordx4 v[34:37], v[34:35], off offset:64
	s_add_u32 s26, s26, 0x10000
	s_addc_u32 s27, s27, 0
	v_lshl_add_u64 v[68:69], s[26:27], 0, v[0:1]
	global_load_dwordx4 v[40:43], v[68:69], off offset:48
	global_load_dwordx4 v[44:47], v[68:69], off offset:32
	global_load_dwordx4 v[48:51], v[68:69], off
	global_load_dwordx4 v[52:55], v[68:69], off offset:16
	global_load_dwordx4 v[56:59], v[68:69], off offset:112
	global_load_dwordx4 v[60:63], v[68:69], off offset:96
	global_load_dwordx4 v[64:67], v[68:69], off offset:80
	s_nop 0
	global_load_dwordx4 v[68:71], v[68:69], off offset:64
	s_add_u32 s26, s26, 0x10000
	s_addc_u32 s27, s27, 0
	v_lshl_add_u64 v[102:103], s[26:27], 0, v[0:1]
	global_load_dwordx4 v[74:77], v[102:103], off offset:48
	global_load_dwordx4 v[78:81], v[102:103], off offset:32
	global_load_dwordx4 v[82:85], v[102:103], off
	global_load_dwordx4 v[86:89], v[102:103], off offset:16
	global_load_dwordx4 v[90:93], v[102:103], off offset:112
	global_load_dwordx4 v[94:97], v[102:103], off offset:96
	global_load_dwordx4 v[98:101], v[102:103], off offset:80
	s_nop 0
	global_load_dwordx4 v[102:105], v[102:103], off offset:64
	s_add_u32 s26, s26, 0x10000
	s_addc_u32 s27, s27, 0
	v_lshl_add_u64 v[136:137], s[26:27], 0, v[0:1]
	global_load_dwordx4 v[108:111], v[136:137], off offset:48
	global_load_dwordx4 v[112:115], v[136:137], off offset:32
	global_load_dwordx4 v[116:119], v[136:137], off
	global_load_dwordx4 v[120:123], v[136:137], off offset:16
	global_load_dwordx4 v[124:127], v[136:137], off offset:112
	global_load_dwordx4 v[128:131], v[136:137], off offset:96
	global_load_dwordx4 v[132:135], v[136:137], off offset:80
	s_nop 0
	global_load_dwordx4 v[136:139], v[136:137], off offset:64
	s_add_u32 s26, s26, 0x10000
	s_addc_u32 s27, s27, 0
	s_waitcnt vmcnt(24)
	v_add_f32_e32 v6, v6, v7
	v_add_f32_e32 v8, v8, v9
	v_mov_b32_e32 v38, v14
	v_mov_b32_e32 v39, v18
	v_mov_b32_e32 v18, v15
	v_pk_add_f32 v[14:15], v[38:39], v[18:19]
	v_mov_b32_e32 v18, v16
	v_mov_b32_e32 v19, v20
	v_mov_b32_e32 v20, v17
	v_pk_add_f32 v[16:17], v[18:19], v[20:21]
	v_mov_b32_e32 v7, v36
	v_pk_add_f32 v[14:15], v[14:15], v[16:17]
	v_mov_b32_e32 v16, v11
	v_mov_b32_e32 v17, v12
	v_mov_b32_e32 v11, v13
	v_pk_add_f32 v[10:11], v[16:17], v[10:11]
	v_add_f32_e32 v5, 0, v14
	v_pk_add_f32 v[10:11], v[10:11], v[10:11] op_sel:[0,1] op_sel_hi:[1,0]
	v_add_f32_e32 v14, v5, v15
	v_mov_b32_e32 v15, v34
	v_mov_b32_e32 v11, v35
	v_mov_b32_e32 v9, v37
	v_pk_add_f32 v[10:11], v[14:15], v[10:11]
	v_pk_add_f32 v[6:7], v[6:7], v[8:9]
	v_mov_b32_e32 v8, v31
	v_mov_b32_e32 v9, v32
	v_mov_b32_e32 v31, v33
	v_pk_add_f32 v[6:7], v[10:11], v[6:7]
	v_pk_add_f32 v[8:9], v[8:9], v[30:31]
	v_pk_add_f32 v[6:7], v[6:7], v[6:7] op_sel:[0,1] op_sel_hi:[1,0]
	v_pk_add_f32 v[8:9], v[8:9], v[8:9] op_sel:[0,1] op_sel_hi:[1,0]
	v_add_f32_e32 v10, v26, v27
	v_add_f32_e32 v12, v28, v29
	v_mov_b32_e32 v7, v22
	v_mov_b32_e32 v9, v23
	v_mov_b32_e32 v11, v24
	v_mov_b32_e32 v13, v25
	v_pk_add_f32 v[6:7], v[6:7], v[8:9]
	v_pk_add_f32 v[8:9], v[10:11], v[12:13]
	s_nop 0
	v_pk_add_f32 v[6:7], v[6:7], v[8:9]
	s_nop 0
	v_add_f32_e32 v5, v6, v7
	v_fmamk_f32 v5, v5, 0x3a000000, v159
	v_rsq_f32_e32 v5, v5
	ds_write_b32 v4, v5
	v_add_u32_e32 v4, 0x800, v4
	s_waitcnt vmcnt(16)
	v_add_f32_e32 v40, v40, v41
	v_add_f32_e32 v42, v42, v43
	v_mov_b32_e32 v72, v48
	v_mov_b32_e32 v73, v52
	v_mov_b32_e32 v52, v49
	v_pk_add_f32 v[48:49], v[72:73], v[52:53]
	v_mov_b32_e32 v52, v50
	v_mov_b32_e32 v53, v54
	v_mov_b32_e32 v54, v51
	v_pk_add_f32 v[50:51], v[52:53], v[54:55]
	v_mov_b32_e32 v41, v70
	v_pk_add_f32 v[48:49], v[48:49], v[50:51]
	v_mov_b32_e32 v50, v45
	v_mov_b32_e32 v51, v46
	v_mov_b32_e32 v45, v47
	v_pk_add_f32 v[44:45], v[50:51], v[44:45]
	v_add_f32_e32 v5, 0, v48
	v_pk_add_f32 v[44:45], v[44:45], v[44:45] op_sel:[0,1] op_sel_hi:[1,0]
	v_add_f32_e32 v48, v5, v49
	v_mov_b32_e32 v49, v68
	v_mov_b32_e32 v45, v69
	v_mov_b32_e32 v43, v71
	v_pk_add_f32 v[44:45], v[48:49], v[44:45]
	v_pk_add_f32 v[40:41], v[40:41], v[42:43]
	v_mov_b32_e32 v42, v65
	v_mov_b32_e32 v43, v66
	v_mov_b32_e32 v65, v67
	v_pk_add_f32 v[40:41], v[44:45], v[40:41]
	v_pk_add_f32 v[42:43], v[42:43], v[64:65]
	v_pk_add_f32 v[40:41], v[40:41], v[40:41] op_sel:[0,1] op_sel_hi:[1,0]
	v_pk_add_f32 v[42:43], v[42:43], v[42:43] op_sel:[0,1] op_sel_hi:[1,0]
	v_add_f32_e32 v44, v60, v61
	v_add_f32_e32 v46, v62, v63
	v_mov_b32_e32 v41, v56
	v_mov_b32_e32 v43, v57
	v_mov_b32_e32 v45, v58
	v_mov_b32_e32 v47, v59
	v_pk_add_f32 v[40:41], v[40:41], v[42:43]
	v_pk_add_f32 v[42:43], v[44:45], v[46:47]
	s_nop 0
	v_pk_add_f32 v[40:41], v[40:41], v[42:43]
	s_nop 0
	v_add_f32_e32 v5, v40, v41
	v_fmamk_f32 v5, v5, 0x3a000000, v159
	v_rsq_f32_e32 v5, v5
	ds_write_b32 v4, v5
	v_add_u32_e32 v4, 0x800, v4
	s_waitcnt vmcnt(8)
	v_add_f32_e32 v74, v74, v75
	v_add_f32_e32 v76, v76, v77
	v_mov_b32_e32 v106, v82
	v_mov_b32_e32 v107, v86
	v_mov_b32_e32 v86, v83
	v_pk_add_f32 v[82:83], v[106:107], v[86:87]
	v_mov_b32_e32 v86, v84
	v_mov_b32_e32 v87, v88
	v_mov_b32_e32 v88, v85
	v_pk_add_f32 v[84:85], v[86:87], v[88:89]
	v_mov_b32_e32 v75, v104
	v_pk_add_f32 v[82:83], v[82:83], v[84:85]
	v_mov_b32_e32 v84, v79
	v_mov_b32_e32 v85, v80
	v_mov_b32_e32 v79, v81
	v_pk_add_f32 v[78:79], v[84:85], v[78:79]
	v_add_f32_e32 v5, 0, v82
	v_pk_add_f32 v[78:79], v[78:79], v[78:79] op_sel:[0,1] op_sel_hi:[1,0]
	v_add_f32_e32 v82, v5, v83
	v_mov_b32_e32 v83, v102
	v_mov_b32_e32 v79, v103
	v_mov_b32_e32 v77, v105
	v_pk_add_f32 v[78:79], v[82:83], v[78:79]
	v_pk_add_f32 v[74:75], v[74:75], v[76:77]
	v_mov_b32_e32 v76, v99
	v_mov_b32_e32 v77, v100
	v_mov_b32_e32 v99, v101
	v_pk_add_f32 v[74:75], v[78:79], v[74:75]
	v_pk_add_f32 v[76:77], v[76:77], v[98:99]
	v_pk_add_f32 v[74:75], v[74:75], v[74:75] op_sel:[0,1] op_sel_hi:[1,0]
	v_pk_add_f32 v[76:77], v[76:77], v[76:77] op_sel:[0,1] op_sel_hi:[1,0]
	v_add_f32_e32 v78, v94, v95
	v_add_f32_e32 v80, v96, v97
	v_mov_b32_e32 v75, v90
	v_mov_b32_e32 v77, v91
	v_mov_b32_e32 v79, v92
	v_mov_b32_e32 v81, v93
	v_pk_add_f32 v[74:75], v[74:75], v[76:77]
	v_pk_add_f32 v[76:77], v[78:79], v[80:81]
	s_nop 0
	v_pk_add_f32 v[74:75], v[74:75], v[76:77]
	s_nop 0
	v_add_f32_e32 v5, v74, v75
	v_fmamk_f32 v5, v5, 0x3a000000, v159
	v_rsq_f32_e32 v5, v5
	ds_write_b32 v4, v5
	v_add_u32_e32 v4, 0x800, v4
	s_waitcnt vmcnt(0)
	v_add_f32_e32 v108, v108, v109
	v_add_f32_e32 v110, v110, v111
	v_mov_b32_e32 v140, v116
	v_mov_b32_e32 v141, v120
	v_mov_b32_e32 v120, v117
	v_pk_add_f32 v[116:117], v[140:141], v[120:121]
	v_mov_b32_e32 v120, v118
	v_mov_b32_e32 v121, v122
	v_mov_b32_e32 v122, v119
	v_pk_add_f32 v[118:119], v[120:121], v[122:123]
	v_mov_b32_e32 v109, v138
	v_pk_add_f32 v[116:117], v[116:117], v[118:119]
	v_mov_b32_e32 v118, v113
	v_mov_b32_e32 v119, v114
	v_mov_b32_e32 v113, v115
	v_pk_add_f32 v[112:113], v[118:119], v[112:113]
	v_add_f32_e32 v5, 0, v116
	v_pk_add_f32 v[112:113], v[112:113], v[112:113] op_sel:[0,1] op_sel_hi:[1,0]
	v_add_f32_e32 v116, v5, v117
	v_mov_b32_e32 v117, v136
	v_mov_b32_e32 v113, v137
	v_mov_b32_e32 v111, v139
	v_pk_add_f32 v[112:113], v[116:117], v[112:113]
	v_pk_add_f32 v[108:109], v[108:109], v[110:111]
	v_mov_b32_e32 v110, v133
	v_mov_b32_e32 v111, v134
	v_mov_b32_e32 v133, v135
	v_pk_add_f32 v[108:109], v[112:113], v[108:109]
	v_pk_add_f32 v[110:111], v[110:111], v[132:133]
	v_pk_add_f32 v[108:109], v[108:109], v[108:109] op_sel:[0,1] op_sel_hi:[1,0]
	v_pk_add_f32 v[110:111], v[110:111], v[110:111] op_sel:[0,1] op_sel_hi:[1,0]
	v_add_f32_e32 v112, v128, v129
	v_add_f32_e32 v114, v130, v131
	v_mov_b32_e32 v109, v124
	v_mov_b32_e32 v111, v125
	v_mov_b32_e32 v113, v126
	v_mov_b32_e32 v115, v127
	v_pk_add_f32 v[108:109], v[108:109], v[110:111]
	v_pk_add_f32 v[110:111], v[112:113], v[114:115]
	s_nop 0
	v_pk_add_f32 v[108:109], v[108:109], v[110:111]
	s_nop 0
	v_add_f32_e32 v5, v108, v109
	v_fmamk_f32 v5, v5, 0x3a000000, v159
	v_rsq_f32_e32 v5, v5
	ds_write_b32 v4, v5
	v_add_u32_e32 v4, 0x800, v4
